# stackF + PRO mod_item k-loop: two 8-row batches per trip, 16 strided loads up front (same FMA order)
# baseline (speedup 1.0000x reference)
; __device__ __forceinline__ void mod_item(const Params& p, int layer, int cc, LAS unsigned char* lds) {
;     ...
;     const float* W = p.w_mod + (size_t)layer * DM * 3072 + cc * 64 + lane;
;     float a0 = 0.f, a1 = 0.f, a2 = 0.f, a3 = 0.f;
; #pragma unroll 8
;     for (int kk = 0; kk < 128; ++kk) { const int k = w * 128 + kk; const float wv = W[(size_t)k * 3072];
;         a0 += sc[k] * wv; a1 += sc[1024 + k] * wv; a2 += sc[2048 + k] * wv; a3 += sc[3072 + k] * wv; }
.LBB0_472:
	v_lshl_add_u64 v[14:15], v[10:11], 0, s[40:41]
	v_add_co_u32_e32 v16, vcc, s19, v14
	s_movk_i32 s5, 0x6000
	s_nop 0
	v_addc_co_u32_e32 v17, vcc, 0, v15, vcc
	v_add_co_u32_e32 v18, vcc, s5, v14
	s_mov_b32 s5, 0x9000
	s_nop 0
	v_addc_co_u32_e32 v19, vcc, 0, v15, vcc
	v_add_co_u32_e32 v20, vcc, s5, v14
	s_mov_b32 s5, 0xc000
	s_nop 0
	v_addc_co_u32_e32 v21, vcc, 0, v15, vcc
	global_load_dword v46, v[14:15], off
	v_add_co_u32_e32 v22, vcc, s5, v14
	s_mov_b32 s5, 0xf000
	s_nop 0
	v_addc_co_u32_e32 v23, vcc, 0, v15, vcc
	v_add_co_u32_e32 v24, vcc, s5, v14
	s_mov_b32 s5, 0x12000
	s_nop 0
	v_addc_co_u32_e32 v25, vcc, 0, v15, vcc
	v_add_co_u32_e32 v26, vcc, s5, v14
	s_mov_b32 s5, 0x15000
	s_nop 0
	v_addc_co_u32_e32 v27, vcc, 0, v15, vcc
	v_add_co_u32_e32 v14, vcc, s5, v14
	s_add_u32 s40, s40, 0x18000
	s_addc_u32 s41, s41, 0
	s_nop 0
	v_addc_co_u32_e32 v15, vcc, 0, v15, vcc
	global_load_dword v48, v[16:17], off
	global_load_dword v50, v[18:19], off
	global_load_dword v52, v[20:21], off
	global_load_dword v54, v[22:23], off
	global_load_dword v56, v[24:25], off
	global_load_dword v58, v[26:27], off
	global_load_dword v60, v[14:15], off
	v_lshl_add_u64 v[14:15], v[10:11], 0, s[40:41]
	v_add_co_u32_e32 v16, vcc, s19, v14
	s_movk_i32 s5, 0x6000
	s_nop 0
	v_addc_co_u32_e32 v17, vcc, 0, v15, vcc
	v_add_co_u32_e32 v18, vcc, s5, v14
	s_mov_b32 s5, 0x9000
	s_nop 0
	v_addc_co_u32_e32 v19, vcc, 0, v15, vcc
	v_add_co_u32_e32 v20, vcc, s5, v14
	s_mov_b32 s5, 0xc000
	s_nop 0
	v_addc_co_u32_e32 v21, vcc, 0, v15, vcc
	global_load_dword v66, v[14:15], off
	v_add_co_u32_e32 v22, vcc, s5, v14
	s_mov_b32 s5, 0xf000
	s_nop 0
	v_addc_co_u32_e32 v23, vcc, 0, v15, vcc
	v_add_co_u32_e32 v24, vcc, s5, v14
	s_mov_b32 s5, 0x12000
	s_nop 0
	v_addc_co_u32_e32 v25, vcc, 0, v15, vcc
	v_add_co_u32_e32 v26, vcc, s5, v14
	s_mov_b32 s5, 0x15000
	s_nop 0
	v_addc_co_u32_e32 v27, vcc, 0, v15, vcc
	v_add_co_u32_e32 v14, vcc, s5, v14
	s_add_u32 s40, s40, 0x18000
	s_addc_u32 s41, s41, 0
	s_nop 0
	v_addc_co_u32_e32 v15, vcc, 0, v15, vcc
	global_load_dword v68, v[16:17], off
	global_load_dword v70, v[18:19], off
	global_load_dword v72, v[20:21], off
	global_load_dword v74, v[22:23], off
	global_load_dword v76, v[24:25], off
	global_load_dword v78, v[26:27], off
	global_load_dword v80, v[14:15], off
	ds_read_b128 v[14:17], v1
	ds_read_b128 v[18:21], v1 offset:16
	ds_read_b128 v[22:25], v1 offset:4096
	ds_read_b128 v[26:29], v1 offset:4112
	ds_read_b128 v[30:33], v1 offset:8192
	ds_read_b128 v[34:37], v1 offset:8208
	ds_read_b128 v[38:41], v1 offset:12288
	ds_read_b128 v[42:45], v1 offset:12304
	s_waitcnt lgkmcnt(7)
	v_mov_b32_e32 v62, v14
	s_waitcnt lgkmcnt(5)
	v_mov_b32_e32 v63, v22
	s_waitcnt lgkmcnt(3)
	v_mov_b32_e32 v64, v30
	s_waitcnt lgkmcnt(1)
	v_mov_b32_e32 v65, v38
	v_mov_b32_e32 v22, v15
	v_mov_b32_e32 v38, v31
	v_mov_b32_e32 v14, v16
	v_mov_b32_e32 v15, v24
	v_mov_b32_e32 v30, v32
	v_mov_b32_e32 v31, v40
	v_mov_b32_e32 v24, v17
	v_mov_b32_e32 v40, v33
	v_mov_b32_e32 v16, v18
	v_mov_b32_e32 v17, v26
	v_mov_b32_e32 v32, v34
	s_waitcnt lgkmcnt(0)
	v_mov_b32_e32 v33, v42
	v_mov_b32_e32 v26, v19
	v_mov_b32_e32 v42, v35
	v_mov_b32_e32 v18, v20
	v_mov_b32_e32 v19, v28
	v_mov_b32_e32 v34, v36
	v_mov_b32_e32 v35, v44
	v_mov_b32_e32 v28, v21
	v_mov_b32_e32 v44, v37
	v_add_u32_e32 v1, 32, v1
	s_waitcnt vmcnt(15)
	v_pk_fma_f32 v[8:9], v[46:47], v[62:63], v[8:9] op_sel_hi:[0,1,1]
	v_pk_fma_f32 v[12:13], v[46:47], v[64:65], v[12:13] op_sel_hi:[0,1,1]
	s_waitcnt vmcnt(14)
	v_pk_fma_f32 v[8:9], v[48:49], v[22:23], v[8:9] op_sel_hi:[0,1,1]
	v_pk_fma_f32 v[12:13], v[48:49], v[38:39], v[12:13] op_sel_hi:[0,1,1]
	s_waitcnt vmcnt(13)
	v_pk_fma_f32 v[8:9], v[50:51], v[14:15], v[8:9] op_sel_hi:[0,1,1]
	v_pk_fma_f32 v[12:13], v[50:51], v[30:31], v[12:13] op_sel_hi:[0,1,1]
	s_waitcnt vmcnt(12)
	v_pk_fma_f32 v[8:9], v[52:53], v[24:25], v[8:9] op_sel_hi:[0,1,1]
	v_pk_fma_f32 v[12:13], v[52:53], v[40:41], v[12:13] op_sel_hi:[0,1,1]
	s_waitcnt vmcnt(11)
	v_pk_fma_f32 v[8:9], v[54:55], v[16:17], v[8:9] op_sel_hi:[0,1,1]
	v_pk_fma_f32 v[12:13], v[54:55], v[32:33], v[12:13] op_sel_hi:[0,1,1]
	s_waitcnt vmcnt(10)
	v_pk_fma_f32 v[8:9], v[56:57], v[26:27], v[8:9] op_sel_hi:[0,1,1]
	v_pk_fma_f32 v[12:13], v[56:57], v[42:43], v[12:13] op_sel_hi:[0,1,1]
	s_waitcnt vmcnt(9)
	v_pk_fma_f32 v[8:9], v[58:59], v[18:19], v[8:9] op_sel_hi:[0,1,1]
	v_pk_fma_f32 v[12:13], v[58:59], v[34:35], v[12:13] op_sel_hi:[0,1,1]
	s_waitcnt vmcnt(8)
	v_pk_fma_f32 v[8:9], v[60:61], v[28:29], v[8:9] op_sel_hi:[0,1,1]
	v_pk_fma_f32 v[12:13], v[60:61], v[44:45], v[12:13] op_sel_hi:[0,1,1]
	ds_read_b128 v[14:17], v1
	ds_read_b128 v[18:21], v1 offset:16
	ds_read_b128 v[22:25], v1 offset:4096
	ds_read_b128 v[26:29], v1 offset:4112
	ds_read_b128 v[30:33], v1 offset:8192
	ds_read_b128 v[34:37], v1 offset:8208
	ds_read_b128 v[38:41], v1 offset:12288
	ds_read_b128 v[42:45], v1 offset:12304
	s_waitcnt lgkmcnt(7)
	v_mov_b32_e32 v62, v14
	s_waitcnt lgkmcnt(5)
	v_mov_b32_e32 v63, v22
	s_waitcnt lgkmcnt(3)
	v_mov_b32_e32 v64, v30
	s_waitcnt lgkmcnt(1)
	v_mov_b32_e32 v65, v38
	v_mov_b32_e32 v22, v15
	v_mov_b32_e32 v38, v31
	v_mov_b32_e32 v14, v16
	v_mov_b32_e32 v15, v24
	v_mov_b32_e32 v30, v32
	v_mov_b32_e32 v31, v40
	v_mov_b32_e32 v24, v17
	v_mov_b32_e32 v40, v33
	v_mov_b32_e32 v16, v18
	v_mov_b32_e32 v17, v26
	v_mov_b32_e32 v32, v34
	s_waitcnt lgkmcnt(0)
	v_mov_b32_e32 v33, v42
	v_mov_b32_e32 v26, v19
	v_mov_b32_e32 v42, v35
	v_mov_b32_e32 v18, v20
	v_mov_b32_e32 v19, v28
	v_mov_b32_e32 v34, v36
	v_mov_b32_e32 v35, v44
	v_mov_b32_e32 v28, v21
	v_mov_b32_e32 v44, v37
	v_add_u32_e32 v1, 32, v1
	s_cmp_eq_u32 s40, 0x180000
	s_waitcnt vmcnt(7)
	v_pk_fma_f32 v[8:9], v[66:67], v[62:63], v[8:9] op_sel_hi:[0,1,1]
	v_pk_fma_f32 v[12:13], v[66:67], v[64:65], v[12:13] op_sel_hi:[0,1,1]
	s_waitcnt vmcnt(6)
	v_pk_fma_f32 v[8:9], v[68:69], v[22:23], v[8:9] op_sel_hi:[0,1,1]
	v_pk_fma_f32 v[12:13], v[68:69], v[38:39], v[12:13] op_sel_hi:[0,1,1]
	s_waitcnt vmcnt(5)
	v_pk_fma_f32 v[8:9], v[70:71], v[14:15], v[8:9] op_sel_hi:[0,1,1]
	v_pk_fma_f32 v[12:13], v[70:71], v[30:31], v[12:13] op_sel_hi:[0,1,1]
	s_waitcnt vmcnt(4)
	v_pk_fma_f32 v[8:9], v[72:73], v[24:25], v[8:9] op_sel_hi:[0,1,1]
	v_pk_fma_f32 v[12:13], v[72:73], v[40:41], v[12:13] op_sel_hi:[0,1,1]
	s_waitcnt vmcnt(3)
	v_pk_fma_f32 v[8:9], v[74:75], v[16:17], v[8:9] op_sel_hi:[0,1,1]
	v_pk_fma_f32 v[12:13], v[74:75], v[32:33], v[12:13] op_sel_hi:[0,1,1]
	s_waitcnt vmcnt(2)
	v_pk_fma_f32 v[8:9], v[76:77], v[26:27], v[8:9] op_sel_hi:[0,1,1]
	v_pk_fma_f32 v[12:13], v[76:77], v[42:43], v[12:13] op_sel_hi:[0,1,1]
	s_waitcnt vmcnt(1)
	v_pk_fma_f32 v[8:9], v[78:79], v[18:19], v[8:9] op_sel_hi:[0,1,1]
	v_pk_fma_f32 v[12:13], v[78:79], v[34:35], v[12:13] op_sel_hi:[0,1,1]
	s_waitcnt vmcnt(0)
	v_pk_fma_f32 v[8:9], v[80:81], v[28:29], v[8:9] op_sel_hi:[0,1,1]
	v_pk_fma_f32 v[12:13], v[80:81], v[44:45], v[12:13] op_sel_hi:[0,1,1]
	s_cbranch_scc0 .LBB0_472
; __device__ __forceinline__ void mod_item(const Params& p, int layer, int cc, LAS unsigned char* lds) {
;     ...
;     red[(w * 4 + 0) * 64 + lane] = a0; red[(w * 4 + 1) * 64 + lane] = a1; red[(w * 4 + 2) * 64 + lane] = a2; red[(w * 4 + 3) * 64 + lane] = a3;
;     __syncthreads();
;     if (t < 256) { const int b = t >> 6, col = t & 63; float s = 0.f;
; #pragma unroll
;         for (int ww = 0; ww < 8; ++ww) s += red[(ww * 4 + b) * 64 + col];
;         ((float*)(p.ws + WS_MOD))[((size_t)layer * 4 + b) * 3072 + cc * 64 + col] = s + p.b_mod[layer * 3072 + cc * 64 + col]; }
	v_lshlrev_b32_e32 v1, 10, v4
	v_lshlrev_b32_e32 v10, 2, v6
	s_movk_i32 s5, 0x100
	v_add3_u32 v1, 0, v1, v10
	v_cmp_gt_i32_e32 vcc, s5, v2
	ds_write2st64_b32 v1, v8, v9 offset0:64 offset1:65
	ds_write2st64_b32 v1, v12, v13 offset0:66 offset1:67
	s_waitcnt lgkmcnt(0)
	s_barrier
	s_and_saveexec_b64 s[40:41], vcc
	s_cbranch_execz .LBB0_423
	s_load_dwordx2 s[20:21], s[0:1], 0x20
	s_mul_i32 s5, s14, 0xc00
	s_add_i32 s5, s26, s5
	v_or_b32_e32 v6, s5, v6
	v_ashrrev_i32_e32 v7, 31, v6
	s_waitcnt lgkmcnt(0)
	v_lshl_add_u64 v[6:7], v[6:7], 2, s[20:21]
	global_load_dword v1, v[6:7], off
	v_and_b32_e32 v6, 0x3fffffc0, v2
	v_lshlrev_b32_e32 v6, 2, v6
	v_readlane_b32 s10, v253, 31
	v_add3_u32 v14, 0, v6, v10
	v_ashrrev_i32_e32 v5, 31, v4
	v_readlane_b32 s11, v253, 32
	ds_read2st64_b32 v[6:7], v14 offset0:64 offset1:68
	ds_read2st64_b32 v[8:9], v14 offset0:72 offset1:76
	ds_read2st64_b32 v[12:13], v14 offset0:80 offset1:84
	ds_read2st64_b32 v[14:15], v14 offset0:88 offset1:92
	v_mov_b64_e32 v[2:3], s[10:11]
	v_lshl_add_u64 v[4:5], s[14:15], 2, v[4:5]
	v_mad_u64_u32 v[2:3], s[14:15], v4, s19, v[2:3]
	s_waitcnt lgkmcnt(3)
	v_add_f32_e32 v4, 0, v6
	v_add_f32_e32 v4, v4, v7
	s_waitcnt lgkmcnt(2)
	v_add_f32_e32 v4, v4, v8
	v_add_f32_e32 v4, v4, v9
	s_waitcnt lgkmcnt(1)
	v_add_f32_e32 v4, v4, v12
	v_add_f32_e32 v4, v4, v13
	v_mad_i32_i24 v3, v5, s19, v3
	s_waitcnt lgkmcnt(0)
	v_add_f32_e32 v4, v4, v14
	v_mov_b32_e32 v11, v0
	v_lshl_add_u64 v[2:3], s[26:27], 2, v[2:3]
	v_add_f32_e32 v4, v4, v15
	v_lshl_add_u64 v[2:3], v[2:3], 0, v[10:11]
	s_waitcnt vmcnt(0)
	v_add_f32_e32 v1, v4, v1
	global_store_dword v[2:3], v1, off
	s_branch .LBB0_423
